# w_cmp table loads to LDS (f32 and bf16 copies): 4 serial load-wait-write trips batched into one round trip each
# baseline (speedup 1.0000x reference)
; #define LAS __attribute__((address_space(3)))
; __device__ __forceinline__ void load_wcmp(const Prm& P, Ctx& C, LAS float* wl) { for (int i = C.tid; i < 32 * 256 / 4; i += NTHR) ((LAS f32x4*)wl)[i] = ((const f32x4*)P.w_cmp)[i]; }
.LBB0_830:
	v_lshl_add_u64 v[12:13], v[0:1], 0, s[4:5]
	v_lshl_add_u64 v[14:15], v[12:13], 0, s[4:5]
	v_lshl_add_u64 v[16:17], v[14:15], 0, s[4:5]
	global_load_dwordx4 v[8:11], v[0:1], off
	global_load_dwordx4 v[20:23], v[12:13], off
	global_load_dwordx4 v[24:27], v[14:15], off
	global_load_dwordx4 v[28:31], v[16:17], off
	s_waitcnt vmcnt(3)
	ds_write_b128 v3, v[8:11]
	s_waitcnt vmcnt(2)
	ds_write_b128 v3, v[20:23] offset:8192
	s_waitcnt vmcnt(1)
	ds_write_b128 v3, v[24:27] offset:16384
	s_waitcnt vmcnt(0)
	ds_write_b128 v3, v[28:31] offset:24576

; #define LAS __attribute__((address_space(3)))
; __device__ __forceinline__ unsigned pk2(float lo, float hi) { return f2bf(lo) | (f2bf(hi) << 16); }
; __device__ __forceinline__ void phase_cmp(const Prm& P, Ctx& C) {
;     ...
;     for (int i = C.tid; i < 32 * 256 / 4; i += NTHR) { const f32x4 w = ((const f32x4*)P.w_cmp)[i]; u32x2 o; o.x = pk2(w[0], w[1]); o.y = pk2(w[2], w[3]); ((LAS u32x2*)wlb)[i] = o; }
.LBB0_1045:
	v_lshl_add_u64 v[20:21], v[0:1], 0, s[4:5]
	v_lshl_add_u64 v[22:23], v[20:21], 0, s[4:5]
	v_lshl_add_u64 v[24:25], v[22:23], 0, s[4:5]
	global_load_dwordx4 v[4:7], v[0:1], off
	global_load_dwordx4 v[8:11], v[20:21], off
	global_load_dwordx4 v[12:15], v[22:23], off
	global_load_dwordx4 v[16:19], v[24:25], off
	s_waitcnt vmcnt(3)
	v_cvt_pk_bf16_f32 v4, v4, v5
	v_cvt_pk_bf16_f32 v5, v6, v7
	ds_write_b64 v3, v[4:5]
	s_waitcnt vmcnt(2)
	v_cvt_pk_bf16_f32 v8, v8, v9
	v_cvt_pk_bf16_f32 v9, v10, v11
	ds_write_b64 v3, v[8:9] offset:4096
	s_waitcnt vmcnt(1)
	v_cvt_pk_bf16_f32 v12, v12, v13
	v_cvt_pk_bf16_f32 v13, v14, v15
	ds_write_b64 v3, v[12:13] offset:8192
	s_waitcnt vmcnt(0)
	v_cvt_pk_bf16_f32 v16, v16, v17
	v_cvt_pk_bf16_f32 v17, v18, v19
	ds_write_b64 v3, v[16:17] offset:12288
